# grid barrier: XCD leader skips buffer_wbl2 after the GEMM phases (all their stores are sc1 write-through)
# speedup vs baseline: 1.0016x; 1.0016x over previous
; #define LAS __attribute__((address_space(3)))
; template <int EPI>
; DI bool tile_coords(int j, int mpx, int& m0, int& n0) {
;   const int x = blockIdx.x & 7, s = blockIdx.x >> 3, ns = gridDim.x >> 3;
;   const int q = s + ns * j;
;   if constexpr (EPI == 0) {
;     if (q >= mpx * 15) return false;
;     const int panel = q / 90, i = q % 90;
;     const int nt = i / 6, mi = i % 6;
;     m0 = (x * mpx + panel * 6 + mi) * 256;
;     n0 = nt * 256;
; __global__ void __launch_bounds__(512, 2) mega(P p) {
;   extern __shared__ __attribute__((aligned(16))) char lds[];
;   __shared__ uint4 xb_words;
;   if (threadIdx.x == 0) xb_words = make_uint4(0u, 0u, 0u, 0u);
;   __syncthreads();
;   const XcdBarrier xb = xcd_barrier_post(p.xbar, (volatile LAS unsigned*)&xb_words);
;   for (int ph = p.pb; ph < p.pe; ++ph) {
;     if (ph == 0) phase_prep(p, lds);
;     else if (ph == 1) phase_h0(p);
;     else {
;       const int l = (ph - 2) >> 2, s = (ph - 2) & 3;
;       if (s == 0) { for (int rr = 0; rr < REP_INPROJ; ++rr) { if (rr) cg::this_grid().sync(); phase_inproj(p, l, lds); } }
.LBB0_5:
	s_or_b64 exec, exec, s[0:1]
	s_load_dwordx2 s[48:49], s[96:97], 0xe0
	s_waitcnt lgkmcnt(0)
	s_cmp_ge_i32 s48, s49
	s_cbranch_scc1 .LBB0_1026
	s_mov_b32 s0, 1
	s_nop 0
	v_writelane_b32 v255, s0, 50
	v_readlane_b32 s1, v254, 0
	s_lshl_b32 s0, s1, 3
	s_add_u32 s76, s96, 0xe8
	s_addc_u32 s77, s97, 0
	s_cmpk_lt_i32 s1, 0x580
	v_writelane_b32 v254, s0, 3
	s_cselect_b64 s[2:3], -1, 0
	v_writelane_b32 v254, s2, 4
	s_lshr_b32 s0, s1, 5
	s_lshr_b32 s84, s1, 3
	v_writelane_b32 v254, s3, 5
	v_writelane_b32 v254, s0, 6
	s_lshl_b32 s0, s1, 5
	s_and_b32 s0, s0, 0x300
	s_and_b32 s5, s1, 7
	v_writelane_b32 v254, s0, 7
	s_lshl_b32 s0, s0, 11
	s_cmpk_lt_u32 s1, 0x870
	v_writelane_b32 v254, s0, 8
	s_cselect_b64 s[0:1], -1, 0
	v_writelane_b32 v254, s0, 9
	v_lshrrev_b32_e32 v1, 20, v0
	v_lshrrev_b32_e32 v0, 10, v0
	v_writelane_b32 v254, s1, 10
	s_mul_i32 s0, s84, 0x2d83
	s_lshr_b32 s0, s0, 20
	s_mul_i32 s1, s0, 0x5a
	s_sub_i32 s1, s84, s1
	s_and_b32 s2, s1, 0xff
	s_mulk_i32 s2, 0xab
	s_bfe_u32 s2, s2, 0x6000a
	s_mul_i32 s3, s2, 6
	s_sub_i32 s1, s1, s3
	s_mul_i32 s3, s5, 18
	s_mul_i32 s0, s0, 6
	s_and_b32 s1, s1, 0xff
	s_add_i32 s0, s3, s0
	s_add_i32 s0, s0, s1
	v_writelane_b32 v254, s5, 11
	s_lshl_b32 s20, s0, 8
	s_lshl_b32 s0, s2, 8
	v_writelane_b32 v254, s3, 12
	s_cmp_lt_i32 s49, 0
	v_writelane_b32 v254, s0, 13
	s_cselect_b64 s[0:1], -1, 0
	v_writelane_b32 v254, s0, 14
	s_mov_b32 s3, 0
	s_mov_b32 s21, s3
	v_writelane_b32 v254, s1, 15
	s_add_u32 s0, s92, 0x200
	s_addc_u32 s1, s93, 0
	s_add_u32 s74, s92, 0x1000
	s_addc_u32 s75, s93, 0
	s_add_u32 s80, s92, 0x1100
	s_addc_u32 s81, s93, 0
	s_add_u32 s82, s92, 0x1200
	s_addc_u32 s83, s93, 0
	s_add_u32 s86, s92, 0x1300
	s_addc_u32 s87, s93, 0
	v_writelane_b32 v254, s0, 16
	s_cmp_eq_u32 s4, 15
	v_or_b32_e32 v0, v0, v1
	v_writelane_b32 v254, s1, 17
	s_cselect_b64 s[0:1], -1, 0
	v_writelane_b32 v254, s0, 18
	s_cmp_eq_u32 s4, 14
	s_load_dwordx16 s[52:67], s[96:97], 0x0
	v_writelane_b32 v254, s1, 19
	s_cselect_b64 s[0:1], -1, 0
	v_writelane_b32 v254, s0, 20
	s_cmp_eq_u32 s4, 13
	s_load_dwordx8 s[40:47], s[96:97], 0xb0
	v_writelane_b32 v254, s1, 21
	s_cselect_b64 s[0:1], -1, 0
	v_writelane_b32 v254, s0, 22
	s_cmp_eq_u32 s4, 12
	v_mbcnt_lo_u32_b32 v2, -1, 0
	v_writelane_b32 v254, s1, 23
	s_cselect_b64 s[0:1], -1, 0
	v_writelane_b32 v254, s0, 24
	s_cmp_eq_u32 s4, 11
	v_mov_b32_e32 v1, 0
	v_writelane_b32 v254, s1, 25
	s_cselect_b64 s[0:1], -1, 0
	v_writelane_b32 v254, s0, 26
	s_cmp_eq_u32 s4, 10
	v_mov_b32_e32 v236, 0x358637bd
	v_writelane_b32 v254, s1, 27
	s_cselect_b64 s[0:1], -1, 0
	v_writelane_b32 v254, s0, 28
	s_cmp_eq_u32 s4, 9
	v_mbcnt_hi_u32_b32 v226, -1, v2
	v_writelane_b32 v254, s1, 29
	s_cselect_b64 s[0:1], -1, 0
	v_writelane_b32 v254, s0, 30
	s_cmp_eq_u32 s4, 8
	v_mov_b32_e32 v194, 0xff800000
	v_writelane_b32 v254, s1, 31
	s_cselect_b64 s[0:1], -1, 0
	v_writelane_b32 v254, s0, 32
	s_cmp_eq_u32 s4, 7
	v_mov_b32_e32 v224, 0x800
	v_writelane_b32 v254, s1, 33
	s_cselect_b64 s[0:1], -1, 0
	v_writelane_b32 v254, s0, 34
	s_cmp_eq_u32 s4, 6
	v_mov_b32_e32 v225, 0x41b17218
	v_writelane_b32 v254, s1, 35
	s_cselect_b64 s[0:1], -1, 0
	v_writelane_b32 v254, s0, 36
	s_cmp_eq_u32 s4, 5
	s_movk_i32 s29, 0x3000
	v_writelane_b32 v254, s1, 37
	s_cselect_b64 s[0:1], -1, 0
	v_writelane_b32 v254, s0, 38
	s_cmp_eq_u32 s4, 4
	s_mov_b32 s37, 0x800000
	v_writelane_b32 v254, s1, 39
	s_cselect_b64 s[0:1], -1, 0
	v_writelane_b32 v254, s0, 40
	s_cmp_eq_u32 s4, 3
	s_mov_b32 s33, 0x20000
	v_writelane_b32 v254, s1, 41
	s_cselect_b64 s[0:1], -1, 0
	v_writelane_b32 v254, s0, 42
	s_cmp_eq_u32 s4, 2
	s_mov_b32 s35, 0x40000
	v_writelane_b32 v254, s1, 43
	s_cselect_b64 s[0:1], -1, 0
	v_writelane_b32 v254, s0, 44
	s_cmp_eq_u32 s4, 1
	s_mov_b32 s39, 0x60000
	v_writelane_b32 v254, s1, 45
	s_cselect_b64 s[0:1], -1, 0
	v_writelane_b32 v254, s0, 46
	s_cmp_eq_u32 s4, 0
	s_mov_b32 s85, 0x10000
	v_writelane_b32 v254, s1, 47
	s_cselect_b64 s[0:1], -1, 0
	v_writelane_b32 v254, s0, 48
	s_movk_i32 s94, 0x4000
	s_movk_i32 s95, 0x80
	v_writelane_b32 v254, s1, 49
	s_lshl_b32 s0, s4, 8
	s_add_u32 s0, s92, s0
	s_addc_u32 s1, s93, 0
	s_add_u32 s4, s0, 0x1400
	s_addc_u32 s5, s1, 0
	v_writelane_b32 v254, s4, 50
	s_add_u32 s0, s0, 0x2400
	s_addc_u32 s1, s1, 0
	v_writelane_b32 v254, s5, 51
	v_writelane_b32 v254, s0, 52
	s_load_dwordx16 s[4:19], s[96:97], 0x70
	s_movk_i32 s79, 0x110
	v_writelane_b32 v254, s1, 53
	s_add_u32 s0, s92, 0x3400
	s_addc_u32 s1, s93, 0
	v_writelane_b32 v254, s0, 54
	s_movk_i32 s30, 0x800
	s_mov_b32 s31, 0x7f800000
	v_writelane_b32 v254, s1, 55
	s_add_u32 s0, s92, 0x3500
	s_addc_u32 s1, s93, 0
	v_writelane_b32 v254, s0, 56
	s_mov_b32 s22, 0x3f317217
	s_mov_b64 s[90:91], 0x1000
	v_writelane_b32 v254, s1, 57
	s_mov_b32 s0, s20
	v_writelane_b32 v254, s0, 58
	s_mov_b32 s34, 0x3fb504f3
	s_mov_b32 s38, 0x3c800000
	v_writelane_b32 v254, s1, 59
	s_lshl_b64 s[0:1], s[20:21], 11
	s_waitcnt lgkmcnt(0)
; #define LAS __attribute__((address_space(3)))
; __global__ void __launch_bounds__(512, 2) mega(P p) {
;   extern __shared__ __attribute__((aligned(16))) char lds[];
;   __shared__ uint4 xb_words;
;   if (threadIdx.x == 0) xb_words = make_uint4(0u, 0u, 0u, 0u);
;   __syncthreads();
;   const XcdBarrier xb = xcd_barrier_post(p.xbar, (volatile LAS unsigned*)&xb_words);
;   for (int ph = p.pb; ph < p.pe; ++ph) {
	s_add_u32 s0, s16, s0
	s_addc_u32 s1, s17, s1
	s_movk_i32 s20, 0x3ff
	s_lshl_b32 s2, s2, 19
	v_and_or_b32 v0, v0, s20, v195
	s_add_u32 s20, s0, 0x20000
	v_writelane_b32 v254, s2, 60
	s_addc_u32 s21, s1, 0
	v_writelane_b32 v254, s20, 61
	s_mov_b32 s28, 0x3e38aa3b
	s_mov_b32 s36, 0x3e8293ee
	v_writelane_b32 v254, s21, 62
	s_add_u32 s20, s0, 0x40000
	s_addc_u32 s21, s1, 0
	v_writelane_b32 v254, s20, 63
	s_nop 1
	v_writelane_b32 v255, s21, 0
	s_add_u32 s20, s0, 0x60000
	v_writelane_b32 v255, s0, 1
	s_addc_u32 s21, s1, 0
	s_add_u32 s88, s64, 0x15000
	v_writelane_b32 v255, s1, 2
	v_writelane_b32 v255, s20, 3
	s_nop 1
	v_writelane_b32 v255, s21, 4
	v_writelane_b32 v255, s52, 5
	s_addc_u32 s89, s65, 0
	s_add_u32 s0, s16, 0x400
	v_writelane_b32 v255, s53, 6
	v_writelane_b32 v255, s54, 7
	v_writelane_b32 v255, s55, 8
	v_writelane_b32 v255, s56, 9
	v_writelane_b32 v255, s57, 10
	v_writelane_b32 v255, s58, 11
	v_writelane_b32 v255, s59, 12
	v_writelane_b32 v255, s60, 13
	v_writelane_b32 v255, s61, 14
	v_writelane_b32 v255, s62, 15
	v_writelane_b32 v255, s63, 16
	v_writelane_b32 v255, s64, 17
	v_writelane_b32 v255, s65, 18
	v_writelane_b32 v255, s66, 19
	v_writelane_b32 v255, s67, 20
	s_addc_u32 s1, s17, 0
	v_writelane_b32 v255, s0, 21
	s_mov_b32 s21, 0x8000
	s_add_i32 s78, 32, 0x10000
	v_writelane_b32 v255, s1, 22
	s_add_i32 s0, 32, 0x18000
	v_writelane_b32 v255, s0, 23
	s_load_dwordx2 s[0:1], s[96:97], 0xd0
	s_mov_b32 s20, 0xff800000
	s_waitcnt lgkmcnt(0)
	v_writelane_b32 v255, s0, 24
	s_nop 1
	v_writelane_b32 v255, s1, 25
	v_cmp_eq_u32_e64 s[0:1], 0, v0
	s_nop 1
	v_writelane_b32 v255, s0, 26
	s_nop 1
	v_writelane_b32 v255, s1, 27
	v_writelane_b32 v255, s40, 28
	s_nop 1
	v_writelane_b32 v255, s41, 29
	v_writelane_b32 v255, s42, 30
	v_writelane_b32 v255, s43, 31
	v_writelane_b32 v255, s44, 32
	v_writelane_b32 v255, s45, 33
	v_writelane_b32 v255, s46, 34
	v_writelane_b32 v255, s47, 35
	s_load_dwordx8 s[40:47], s[96:97], 0x40
	s_waitcnt lgkmcnt(0)
	v_writelane_b32 v255, s40, 36
	s_nop 1
	v_writelane_b32 v255, s41, 37
	v_writelane_b32 v255, s42, 38
	v_writelane_b32 v255, s43, 39
	v_writelane_b32 v255, s44, 40
	v_writelane_b32 v255, s45, 41
	v_writelane_b32 v255, s46, 42
	v_writelane_b32 v255, s47, 43
	v_writelane_b32 v255, s86, 44
	s_nop 1
	v_writelane_b32 v255, s87, 45
	v_writelane_b32 v255, s88, 46
	s_nop 1
	v_writelane_b32 v255, s89, 47
	v_writelane_b32 v255, s80, 48
	s_nop 1
	v_writelane_b32 v255, s81, 49
	s_branch .LBB0_10

; __device__ __forceinline__ unsigned xb_ld(unsigned* p)              { return __hip_atomic_load(p, __ATOMIC_RELAXED, __HIP_MEMORY_SCOPE_AGENT); }
; __device__ __forceinline__ unsigned xb_add(unsigned* p, unsigned v) { return __hip_atomic_fetch_add(p, v, __ATOMIC_RELAXED, __HIP_MEMORY_SCOPE_AGENT); }
; #define XB_SPIN(cond, bar) do { unsigned _sp = 0; while (cond) { __builtin_amdgcn_s_sleep(1); \
;     if ((++_sp & 255u) == 0u) { if (xb_ld(&(bar)[XB_TMO])) break; if (_sp > XB_SPIN_CAP) { atomicAdd(&(bar)[XB_TMO], 1u); break; } } } } while (0)
; __device__ __forceinline__ void xcd_barrier(const XcdBarrier& b) {
;     ...
;         const unsigned old = xb_add(&bar[XB_XSUB(b.x)], 1u);
;         const unsigned gen = old / nloc;
;         if (old + 1u == (gen + 1u) * nloc) {
;             __builtin_amdgcn_fence(__ATOMIC_RELEASE, "agent");
;             asm volatile("s_waitcnt vmcnt(0)" ::: "memory");
;             const unsigned og = xb_add(&bar[XB_TOP], 1u);
;             const unsigned tg = og / nx;
;             if (og + 1u == (tg + 1u) * nx) xb_add(&bar[XB_TOPGEN], 1u);
;             else XB_SPIN(xb_ld(&bar[XB_TOPGEN]) == tg, bar);
;             __builtin_amdgcn_fence(__ATOMIC_ACQUIRE, "agent");
;             xb_add(&bar[XB_XGEN(b.x)], 1u);
;             asm volatile("s_waitcnt vmcnt(0)" ::: "memory");
.LBB0_1007:
	s_andn2_saveexec_b64 s[24:25], s[40:41]
	s_cbranch_execz .LBB0_8
	s_mov_b64 s[40:41], exec
	v_readlane_b32 s2, v255, 50
	s_bitcmp0_b32 s2, 0
	s_cbranch_scc1 .Lbar_nowb
	buffer_wbl2 sc1
.Lbar_nowb:
	s_waitcnt lgkmcnt(0)
	s_waitcnt vmcnt(0)
	v_mbcnt_lo_u32_b32 v0, s40, 0
	v_mbcnt_hi_u32_b32 v0, s41, v0
	v_cmp_eq_u32_e32 vcc, 0, v0
	s_and_saveexec_b64 s[42:43], vcc
	s_cbranch_execz .LBB0_1010
	s_bcnt1_i32_b64 s2, s[40:41]
	v_readlane_b32 s24, v254, 54
	v_mov_b32_e32 v3, s2
	v_readlane_b32 s25, v254, 55
	s_nop 4
	global_atomic_add v3, v1, v3, s[24:25] sc0
